# phase0 adaLN weight loads de-serialised (16 in flight) + in-proj GEMM v4 without de-phase sleep
# speedup vs baseline: 1.0352x; 1.0352x over previous
.LBB0_75:
	v_lshl_add_u64 v[112:113], v[92:93], 0, v[28:29]
	global_load_dword v128, v[112:113], off nt
	v_lshl_add_u64 v[112:113], v[90:91], 0, v[28:29]
	global_load_dword v129, v[112:113], off nt
	v_lshl_add_u64 v[112:113], v[88:89], 0, v[28:29]
	global_load_dword v130, v[112:113], off nt
	v_lshl_add_u64 v[112:113], v[86:87], 0, v[28:29]
	global_load_dword v131, v[112:113], off nt
	v_lshl_add_u64 v[112:113], v[84:85], 0, v[28:29]
	global_load_dword v132, v[112:113], off nt
	v_lshl_add_u64 v[112:113], v[82:83], 0, v[28:29]
	global_load_dword v133, v[112:113], off nt
	v_lshl_add_u64 v[112:113], v[18:19], 0, v[28:29]
	global_load_dword v134, v[112:113], off nt
	v_lshl_add_u64 v[112:113], v[16:17], 0, v[28:29]
	global_load_dword v135, v[112:113], off nt
	v_lshl_add_u64 v[112:113], v[14:15], 0, v[28:29]
	global_load_dword v136, v[112:113], off nt
	v_lshl_add_u64 v[112:113], v[12:13], 0, v[28:29]
	global_load_dword v137, v[112:113], off nt
	v_lshl_add_u64 v[112:113], v[10:11], 0, v[28:29]
	global_load_dword v138, v[112:113], off nt
	v_lshl_add_u64 v[112:113], v[8:9], 0, v[28:29]
	global_load_dword v139, v[112:113], off nt
	v_lshl_add_u64 v[112:113], v[6:7], 0, v[28:29]
	global_load_dword v140, v[112:113], off nt
	v_lshl_add_u64 v[112:113], v[4:5], 0, v[28:29]
	global_load_dword v141, v[112:113], off nt
	v_lshl_add_u64 v[112:113], v[2:3], 0, v[28:29]
	global_load_dword v142, v[112:113], off nt
	v_lshl_add_u64 v[112:113], v[0:1], 0, v[28:29]
	global_load_dword v143, v[112:113], off nt
	v_add_u32_e32 v109, 0x1000, v64
	v_add_u32_e32 v110, 0x2000, v64
	ds_read2_b32 v[116:117], v109 offset1:8
	ds_read2_b32 v[118:119], v110 offset1:8
	ds_read2_b32 v[114:115], v64 offset1:8
	v_add_u32_e32 v47, 0x80, v47
	s_movk_i32 s15, 0x37f
	s_waitcnt lgkmcnt(2)
	v_mov_b32_e32 v121, v116
	s_waitcnt lgkmcnt(1)
	v_mov_b32_e32 v120, v118
	v_mov_b32_e32 v116, v119
	v_cmp_lt_i32_e32 vcc, s15, v47
	v_lshl_add_u64 v[92:93], v[92:93], 0, s[54:55]
	s_or_b64 s[44:45], vcc, s[44:45]
	s_waitcnt vmcnt(15)
	v_mov_b32_e32 v112, v128
	v_pk_fma_f32 v[120:121], v[112:113], v[120:121], v[96:97] op_sel_hi:[0,1,1]
	v_add_u32_e32 v96, 0x3000, v64
	v_add_u32_e32 v97, 0x4000, v64
	ds_read2_b32 v[122:123], v96 offset1:8
	ds_read2_b32 v[124:125], v97 offset1:8
	s_waitcnt lgkmcnt(2)
	v_fmac_f32_e32 v41, v112, v114
	s_waitcnt lgkmcnt(1)
	v_mov_b32_e32 v127, v122
	s_waitcnt lgkmcnt(0)
	v_mov_b32_e32 v126, v124
	v_pk_fma_f32 v[94:95], v[112:113], v[126:127], v[94:95] op_sel_hi:[0,1,1]
	v_mov_b32_e32 v122, v125
	v_lshl_add_u64 v[90:91], v[90:91], 0, s[54:55]
	s_waitcnt vmcnt(14)
	v_mov_b32_e32 v112, v129
	v_fmac_f32_e32 v41, v112, v115
	v_pk_fma_f32 v[114:115], v[112:113], v[116:117], v[120:121] op_sel_hi:[0,1,1]
	v_pk_fma_f32 v[94:95], v[112:113], v[122:123], v[94:95] op_sel_hi:[0,1,1]
	ds_read2_b32 v[116:117], v64 offset0:16 offset1:24
	ds_read2_b32 v[118:119], v109 offset0:16 offset1:24
	ds_read2_b32 v[120:121], v110 offset0:16 offset1:24
	v_lshl_add_u64 v[88:89], v[88:89], 0, s[54:55]
	s_waitcnt lgkmcnt(1)
	v_mov_b32_e32 v123, v118
	s_waitcnt lgkmcnt(0)
	v_mov_b32_e32 v122, v120
	v_mov_b32_e32 v118, v121
	s_waitcnt vmcnt(13)
	v_mov_b32_e32 v112, v130
	v_pk_fma_f32 v[114:115], v[112:113], v[122:123], v[114:115] op_sel_hi:[0,1,1]
	ds_read2_b32 v[122:123], v96 offset0:16 offset1:24
	ds_read2_b32 v[124:125], v97 offset0:16 offset1:24
	v_fmac_f32_e32 v41, v112, v116
	s_waitcnt lgkmcnt(1)
	v_mov_b32_e32 v127, v122
	s_waitcnt lgkmcnt(0)
	v_mov_b32_e32 v126, v124
	v_pk_fma_f32 v[94:95], v[112:113], v[126:127], v[94:95] op_sel_hi:[0,1,1]
	v_mov_b32_e32 v122, v125
	v_lshl_add_u64 v[86:87], v[86:87], 0, s[54:55]
	s_waitcnt vmcnt(12)
	v_mov_b32_e32 v112, v131
	v_fmac_f32_e32 v41, v112, v117
	v_pk_fma_f32 v[114:115], v[112:113], v[118:119], v[114:115] op_sel_hi:[0,1,1]
	v_pk_fma_f32 v[94:95], v[112:113], v[122:123], v[94:95] op_sel_hi:[0,1,1]
	ds_read2_b32 v[116:117], v64 offset0:32 offset1:40
	ds_read2_b32 v[118:119], v109 offset0:32 offset1:40
	ds_read2_b32 v[120:121], v110 offset0:32 offset1:40
	v_lshl_add_u64 v[84:85], v[84:85], 0, s[54:55]
	s_waitcnt lgkmcnt(1)
	v_mov_b32_e32 v123, v118
	s_waitcnt lgkmcnt(0)
	v_mov_b32_e32 v122, v120
	v_mov_b32_e32 v118, v121
	s_waitcnt vmcnt(11)
	v_mov_b32_e32 v112, v132
	v_pk_fma_f32 v[114:115], v[112:113], v[122:123], v[114:115] op_sel_hi:[0,1,1]
	ds_read2_b32 v[122:123], v96 offset0:32 offset1:40
	ds_read2_b32 v[124:125], v97 offset0:32 offset1:40
	v_fmac_f32_e32 v41, v112, v116
	s_waitcnt lgkmcnt(1)
	v_mov_b32_e32 v127, v122
	s_waitcnt lgkmcnt(0)
	v_mov_b32_e32 v126, v124
	v_pk_fma_f32 v[94:95], v[112:113], v[126:127], v[94:95] op_sel_hi:[0,1,1]
	v_mov_b32_e32 v122, v125
	v_lshl_add_u64 v[82:83], v[82:83], 0, s[54:55]
	s_waitcnt vmcnt(10)
	v_mov_b32_e32 v112, v133
	v_fmac_f32_e32 v41, v112, v117
	v_pk_fma_f32 v[114:115], v[112:113], v[118:119], v[114:115] op_sel_hi:[0,1,1]
	v_pk_fma_f32 v[94:95], v[112:113], v[122:123], v[94:95] op_sel_hi:[0,1,1]
	ds_read2_b32 v[116:117], v64 offset0:48 offset1:56
	ds_read2_b32 v[118:119], v109 offset0:48 offset1:56
	ds_read2_b32 v[120:121], v110 offset0:48 offset1:56
	v_lshl_add_u64 v[18:19], v[18:19], 0, s[54:55]
	s_waitcnt lgkmcnt(1)
	v_mov_b32_e32 v123, v118
	s_waitcnt lgkmcnt(0)
	v_mov_b32_e32 v122, v120
	v_mov_b32_e32 v118, v121
	s_waitcnt vmcnt(9)
	v_mov_b32_e32 v112, v134
	v_pk_fma_f32 v[114:115], v[112:113], v[122:123], v[114:115] op_sel_hi:[0,1,1]
	ds_read2_b32 v[122:123], v96 offset0:48 offset1:56
	ds_read2_b32 v[124:125], v97 offset0:48 offset1:56
	v_fmac_f32_e32 v41, v112, v116
	s_waitcnt lgkmcnt(1)
	v_mov_b32_e32 v127, v122
	s_waitcnt lgkmcnt(0)
	v_mov_b32_e32 v126, v124
	v_pk_fma_f32 v[94:95], v[112:113], v[126:127], v[94:95] op_sel_hi:[0,1,1]
	v_mov_b32_e32 v122, v125
	v_lshl_add_u64 v[16:17], v[16:17], 0, s[54:55]
	s_waitcnt vmcnt(8)
	v_mov_b32_e32 v112, v135
	v_fmac_f32_e32 v41, v112, v117
	v_pk_fma_f32 v[114:115], v[112:113], v[118:119], v[114:115] op_sel_hi:[0,1,1]
	v_pk_fma_f32 v[94:95], v[112:113], v[122:123], v[94:95] op_sel_hi:[0,1,1]
	ds_read2_b32 v[116:117], v64 offset0:64 offset1:72
	ds_read2_b32 v[118:119], v109 offset0:64 offset1:72
	ds_read2_b32 v[120:121], v110 offset0:64 offset1:72
	v_lshl_add_u64 v[14:15], v[14:15], 0, s[54:55]
	s_waitcnt lgkmcnt(1)
	v_mov_b32_e32 v123, v118
	s_waitcnt lgkmcnt(0)
	v_mov_b32_e32 v122, v120
	v_mov_b32_e32 v118, v121
	s_waitcnt vmcnt(7)
	v_mov_b32_e32 v112, v136
	v_pk_fma_f32 v[114:115], v[112:113], v[122:123], v[114:115] op_sel_hi:[0,1,1]
	ds_read2_b32 v[122:123], v96 offset0:64 offset1:72
	ds_read2_b32 v[124:125], v97 offset0:64 offset1:72
	v_fmac_f32_e32 v41, v112, v116
	s_waitcnt lgkmcnt(1)
	v_mov_b32_e32 v127, v122
	s_waitcnt lgkmcnt(0)
	v_mov_b32_e32 v126, v124
	v_pk_fma_f32 v[94:95], v[112:113], v[126:127], v[94:95] op_sel_hi:[0,1,1]
	v_mov_b32_e32 v122, v125
	v_lshl_add_u64 v[12:13], v[12:13], 0, s[54:55]
	s_waitcnt vmcnt(6)
	v_mov_b32_e32 v112, v137
	v_fmac_f32_e32 v41, v112, v117
	v_pk_fma_f32 v[114:115], v[112:113], v[118:119], v[114:115] op_sel_hi:[0,1,1]
	v_pk_fma_f32 v[94:95], v[112:113], v[122:123], v[94:95] op_sel_hi:[0,1,1]
	ds_read2_b32 v[116:117], v64 offset0:80 offset1:88
	ds_read2_b32 v[118:119], v109 offset0:80 offset1:88
	ds_read2_b32 v[120:121], v110 offset0:80 offset1:88
	v_lshl_add_u64 v[10:11], v[10:11], 0, s[54:55]
	s_waitcnt lgkmcnt(1)
	v_mov_b32_e32 v123, v118
	s_waitcnt lgkmcnt(0)
	v_mov_b32_e32 v122, v120
	v_mov_b32_e32 v118, v121
	s_waitcnt vmcnt(5)
	v_mov_b32_e32 v112, v138
	v_pk_fma_f32 v[114:115], v[112:113], v[122:123], v[114:115] op_sel_hi:[0,1,1]
	ds_read2_b32 v[122:123], v96 offset0:80 offset1:88
	ds_read2_b32 v[124:125], v97 offset0:80 offset1:88
	v_fmac_f32_e32 v41, v112, v116
	s_waitcnt lgkmcnt(1)
	v_mov_b32_e32 v127, v122
	s_waitcnt lgkmcnt(0)
	v_mov_b32_e32 v126, v124
	v_pk_fma_f32 v[94:95], v[112:113], v[126:127], v[94:95] op_sel_hi:[0,1,1]
	v_mov_b32_e32 v122, v125
	v_lshl_add_u64 v[8:9], v[8:9], 0, s[54:55]
	s_waitcnt vmcnt(4)
	v_mov_b32_e32 v112, v139
	v_fmac_f32_e32 v41, v112, v117
	v_pk_fma_f32 v[114:115], v[112:113], v[118:119], v[114:115] op_sel_hi:[0,1,1]
	v_pk_fma_f32 v[94:95], v[112:113], v[122:123], v[94:95] op_sel_hi:[0,1,1]
	ds_read2_b32 v[116:117], v64 offset0:96 offset1:104
	ds_read2_b32 v[118:119], v109 offset0:96 offset1:104
	ds_read2_b32 v[120:121], v110 offset0:96 offset1:104
	v_lshl_add_u64 v[6:7], v[6:7], 0, s[54:55]
	s_waitcnt lgkmcnt(1)
	v_mov_b32_e32 v123, v118
	s_waitcnt lgkmcnt(0)
	v_mov_b32_e32 v122, v120
	v_mov_b32_e32 v118, v121
	s_waitcnt vmcnt(3)
	v_mov_b32_e32 v112, v140
	v_pk_fma_f32 v[114:115], v[112:113], v[122:123], v[114:115] op_sel_hi:[0,1,1]
	ds_read2_b32 v[122:123], v96 offset0:96 offset1:104
	ds_read2_b32 v[124:125], v97 offset0:96 offset1:104
	v_fmac_f32_e32 v41, v112, v116
	s_waitcnt lgkmcnt(1)
	v_mov_b32_e32 v127, v122
	s_waitcnt lgkmcnt(0)
	v_mov_b32_e32 v126, v124
	v_pk_fma_f32 v[94:95], v[112:113], v[126:127], v[94:95] op_sel_hi:[0,1,1]
	v_mov_b32_e32 v122, v125
	v_lshl_add_u64 v[4:5], v[4:5], 0, s[54:55]
	s_waitcnt vmcnt(2)
	v_mov_b32_e32 v112, v141
	v_fmac_f32_e32 v41, v112, v117
	v_pk_fma_f32 v[114:115], v[112:113], v[118:119], v[114:115] op_sel_hi:[0,1,1]
	v_pk_fma_f32 v[94:95], v[112:113], v[122:123], v[94:95] op_sel_hi:[0,1,1]
	ds_read2_b32 v[116:117], v64 offset0:112 offset1:120
	ds_read2_b32 v[118:119], v109 offset0:112 offset1:120
	ds_read2_b32 v[120:121], v110 offset0:112 offset1:120
	v_lshl_add_u64 v[2:3], v[2:3], 0, s[54:55]
	v_add_u32_e32 v64, 0x200, v64
	s_waitcnt lgkmcnt(1)
	v_mov_b32_e32 v123, v118
	s_waitcnt lgkmcnt(0)
	v_mov_b32_e32 v122, v120
	v_mov_b32_e32 v118, v121
	s_waitcnt vmcnt(1)
	v_mov_b32_e32 v112, v142
	v_pk_fma_f32 v[114:115], v[112:113], v[122:123], v[114:115] op_sel_hi:[0,1,1]
	ds_read2_b32 v[122:123], v96 offset0:112 offset1:120
	ds_read2_b32 v[124:125], v97 offset0:112 offset1:120
	v_fmac_f32_e32 v41, v112, v116
	s_waitcnt lgkmcnt(1)
	v_mov_b32_e32 v97, v122
	s_waitcnt lgkmcnt(0)
	v_mov_b32_e32 v96, v124
	v_pk_fma_f32 v[94:95], v[112:113], v[96:97], v[94:95] op_sel_hi:[0,1,1]
	v_mov_b32_e32 v122, v125
	v_lshl_add_u64 v[0:1], v[0:1], 0, s[54:55]
	s_waitcnt vmcnt(0)
	v_mov_b32_e32 v110, v143
	v_fmac_f32_e32 v41, v110, v117
	v_pk_fma_f32 v[96:97], v[110:111], v[118:119], v[114:115] op_sel_hi:[0,1,1]
	v_pk_fma_f32 v[94:95], v[110:111], v[122:123], v[94:95] op_sel_hi:[0,1,1]
	s_andn2_b64 exec, exec, s[44:45]
	s_cbranch_execnz .LBB0_75
	s_or_b64 exec, exec, s[44:45]

.LBB0_268:
	s_or_b64 exec, exec, s[0:1]
	v_readlane_b32 s0, v254, 29
	v_readlane_b32 s1, v254, 30
	s_waitcnt lgkmcnt(0)
	v_mov_b32_e32 v0, v193
	s_and_b64 vcc, exec, s[0:1]
	s_barrier
	s_cbranch_vccz .LBB0_270
.LBB0_270:
	s_and_b64 s[0:1], s[20:21], exec
	s_mov_b32 s10, 208
	s_mov_b32 s11, 20648882
	s_mov_b32 s12, 6656
	s_mov_b32 s1, 2496
	s_cmov_b32 s10, 168
	s_cmov_b32 s11, 25565282
	s_cmov_b32 s12, 5376
	s_cmov_b32 s1, 2016
	v_readlane_b32 s28, v252, 0
	v_readlane_b32 s6, v252, 1
	s_lshr_b32 s6, s6, 3
	s_and_b32 s0, s28, 7
	s_mul_i32 s0, s0, s6
	s_lshr_b32 s28, s28, 3
	s_add_u32 s0, s0, s28
	s_lshl_b32 s6, s6, 3
	s_cmp_ge_u32 s0, s1
	s_cbranch_scc1 .Lgin_done
	v_and_b32_e32 v128, 31, v193
	v_lshlrev_b32_e32 v129, 7, v128
	v_bfe_u32 v130, v193, 1, 3
	v_bfe_u32 v131, v193, 5, 1
	v_xor_b32_e32 v130, v130, v131
	v_bfe_u32 v131, v193, 7, 1
	v_lshl_add_u32 v131, v131, 14, v129
	v_bfe_u32 v132, v193, 6, 1
	v_lshl_add_u32 v132, v132, 13, v129
	v_lshl_add_u32 v144, v130, 4, v131
	v_lshl_add_u32 v211, v130, 4, v132
	v_xor_b32_e32 v128, 2, v130
	v_lshl_add_u32 v146, v128, 4, v131
	v_lshl_add_u32 v248, v128, 4, v132
	v_xor_b32_e32 v128, 4, v130
	v_lshl_add_u32 v147, v128, 4, v131
	v_lshl_add_u32 v249, v128, 4, v132
	v_xor_b32_e32 v128, 6, v130
	v_lshl_add_u32 v210, v128, 4, v131
	v_lshl_add_u32 v250, v128, 4, v132
	v_and_b32_e32 v128, 7, v193
	v_bfe_u32 v129, v193, 4, 3
	v_xor_b32_e32 v128, v128, v129
	v_lshrrev_b32_e32 v129, 3, v193
	v_lshlrev_b32_e32 v129, 11, v129
	v_lshl_add_u32 v251, v128, 4, v129
	v_lshrrev_b32_e32 v128, 6, v193
	v_lshlrev_b32_e32 v128, 10, v128
	s_nop 0
	v_readfirstlane_b32 s22, v128
	v_and_b32_e32 v129, 63, v193
	v_lshl_add_u32 v128, v129, 12, v128
	v_add_u32_e32 v145, 1020, v128
